# indexer work table rebalanced with measured per-item cost model (XCD-local batches kept)
# speedup vs baseline: 1.0184x; 1.0033x over previous
_ZL7idx_tab:
	.short	32
	.short	217
	.short	144
	.short	65535
	.short	65535
	.short	477
	.short	409
	.short	339
	.short	65535
	.short	65535
	.short	671
	.short	600
	.short	723
	.short	65535
	.short	65535
	.short	416
	.short	798
	.short	782
	.short	65535
	.short	65535
	.short	1182
	.short	1111
	.short	1238
	.short	1090
	.short	65535
	.short	1311
	.short	1370
	.short	1425
	.short	65535
	.short	65535
	.short	1757
	.short	1754
	.short	1746
	.short	65535
	.short	65535
	.short	1950
	.short	1948
	.short	1936
	.short	65535
	.short	65535
	.short	28
	.short	153
	.short	147
	.short	0
	.short	65535
	.short	224
	.short	343
	.short	470
	.short	65535
	.short	65535
	.short	352
	.short	664
	.short	530
	.short	65535
	.short	65535
	.short	863
	.short	858
	.short	977
	.short	65535
	.short	65535
	.short	1244
	.short	1178
	.short	1172
	.short	65535
	.short	65535
	.short	1374
	.short	1368
	.short	1428
	.short	65535
	.short	65535
	.short	1567
	.short	1626
	.short	1744
	.short	65535
	.short	65535
	.short	2014
	.short	2011
	.short	1937
	.short	65535
	.short	65535
	.short	94
	.short	23
	.short	215
	.short	130
	.short	65535
	.short	411
	.short	345
	.short	404
	.short	322
	.short	65535
	.short	543
	.short	602
	.short	721
	.short	65535
	.short	65535
	.short	862
	.short	988
	.short	783
	.short	898
	.short	962
	.short	608
	.short	1052
	.short	1039
	.short	1154
	.short	65535
	.short	1306
	.short	1369
	.short	1427
	.short	1410
	.short	1472
	.short	800
	.short	1621
	.short	1684
	.short	1666
	.short	1603
	.short	1885
	.short	2007
	.short	2006
	.short	1922
	.short	1794
	.short	93
	.short	92
	.short	81
	.short	65535
	.short	65535
	.short	351
	.short	342
	.short	469
	.short	450
	.short	259
	.short	606
	.short	603
	.short	591
	.short	706
	.short	705
	.short	480
	.short	990
	.short	847
	.short	65535
	.short	65535
	.short	1119
	.short	1054
	.short	1102
	.short	1218
	.short	65535
	.short	1309
	.short	1500
	.short	1424
	.short	65535
	.short	65535
	.short	1631
	.short	1564
	.short	1742
	.short	1730
	.short	1537
	.short	1887
	.short	1819
	.short	1871
	.short	1986
	.short	1795
	.short	96
	.short	85
	.short	84
	.short	131
	.short	3
	.short	413
	.short	284
	.short	401
	.short	65535
	.short	65535
	.short	734
	.short	540
	.short	655
	.short	643
	.short	577
	.short	927
	.short	796
	.short	911
	.short	899
	.short	65535
	.short	1183
	.short	1245
	.short	1167
	.short	65535
	.short	65535
	.short	1439
	.short	1371
	.short	1296
	.short	65535
	.short	65535
	.short	1695
	.short	1561
	.short	1745
	.short	65535
	.short	65535
	.short	1951
	.short	1821
	.short	1935
	.short	1923
	.short	65535
	.short	219
	.short	218
	.short	83
	.short	195
	.short	65535
	.short	479
	.short	407
	.short	405
	.short	451
	.short	65535
	.short	735
	.short	670
	.short	718
	.short	707
	.short	65535
	.short	925
	.short	792
	.short	979
	.short	963
	.short	65535
	.short	1246
	.short	1047
	.short	1173
	.short	1219
	.short	1155
	.short	672
	.short	1367
	.short	1302
	.short	65535
	.short	65535
	.short	1759
	.short	1693
	.short	1743
	.short	1731
	.short	65535
	.short	1949
	.short	1946
	.short	2001
	.short	1987
	.short	65535
	.short	30
	.short	151
	.short	86
	.short	2
	.short	65535
	.short	286
	.short	344
	.short	338
	.short	258
	.short	65535
	.short	668
	.short	730
	.short	596
	.short	65535
	.short	65535
	.short	987
	.short	922
	.short	853
	.short	65535
	.short	65535
	.short	1051
	.short	1114
	.short	1043
	.short	1026
	.short	65535
	.short	1310
	.short	1498
	.short	1490
	.short	65535
	.short	65535
	.short	1566
	.short	1624
	.short	1554
	.short	1538
	.short	65535
	.short	1822
	.short	1884
	.short	2000
	.short	65535
	.short	65535
	.short	31
	.short	87
	.short	150
	.short	66
	.short	65535
	.short	350
	.short	346
	.short	274
	.short	65535
	.short	65535
	.short	288
	.short	537
	.short	527
	.short	578
	.short	642
	.short	799
	.short	986
	.short	785
	.short	65535
	.short	65535
	.short	1116
	.short	1113
	.short	1108
	.short	65535
	.short	65535
	.short	736
	.short	1308
	.short	1357
	.short	1346
	.short	1411
	.short	1629
	.short	1627
	.short	1617
	.short	65535
	.short	65535
	.short	928
	.short	1814
	.short	1813
	.short	1858
	.short	65535
	.short	158
	.short	90
	.short	146
	.short	65535
	.short	65535
	.short	414
	.short	347
	.short	464
	.short	65535
	.short	65535
	.short	542
	.short	541
	.short	654
	.short	515
	.short	576
	.short	926
	.short	920
	.short	784
	.short	771
	.short	835
	.short	544
	.short	1242
	.short	1166
	.short	1027
	.short	1088
	.short	1503
	.short	1436
	.short	1422
	.short	1283
	.short	1409
	.short	1694
	.short	1625
	.short	1682
	.short	65535
	.short	65535
	.short	1886
	.short	2009
	.short	1811
	.short	65535
	.short	65535
	.short	223
	.short	222
	.short	206
	.short	67
	.short	65535
	.short	478
	.short	280
	.short	466
	.short	323
	.short	65535
	.short	607
	.short	663
	.short	532
	.short	579
	.short	514
	.short	860
	.short	794
	.short	978
	.short	769
	.short	65535
	.short	1247
	.short	1112
	.short	1041
	.short	1091
	.short	65535
	.short	1438
	.short	1437
	.short	1486
	.short	1347
	.short	1474
	.short	1565
	.short	1562
	.short	1683
	.short	65535
	.short	65535
	.short	2015
	.short	2013
	.short	1999
	.short	1859
	.short	65535
	.short	29
	.short	91
	.short	16
	.short	128
	.short	65535
	.short	287
	.short	285
	.short	269
	.short	256
	.short	384
	.short	733
	.short	727
	.short	599
	.short	640
	.short	65535
	.short	797
	.short	919
	.short	791
	.short	896
	.short	65535
	.short	1118
	.short	1053
	.short	1037
	.short	1024
	.short	1152
	.short	1375
	.short	1499
	.short	1359
	.short	1280
	.short	1408
	.short	1758
	.short	1686
	.short	1622
	.short	1536
	.short	1664
	.short	1883
	.short	1879
	.short	1943
	.short	1792
	.short	1920
	.short	95
	.short	159
	.short	77
	.short	192
	.short	65535
	.short	349
	.short	283
	.short	273
	.short	65535
	.short	65535
	.short	732
	.short	666
	.short	594
	.short	704
	.short	65535
	.short	861
	.short	984
	.short	851
	.short	960
	.short	65535
	.short	1179
	.short	1050
	.short	1107
	.short	1216
	.short	65535
	.short	1373
	.short	1497
	.short	1363
	.short	65535
	.short	65535
	.short	1630
	.short	1751
	.short	1685
	.short	1600
	.short	1728
	.short	992
	.short	2010
	.short	1869
	.short	1856
	.short	1984
	.short	157
	.short	214
	.short	148
	.short	1
	.short	129
	.short	415
	.short	410
	.short	462
	.short	257
	.short	385
	.short	669
	.short	598
	.short	534
	.short	513
	.short	641
	.short	991
	.short	855
	.short	854
	.short	65535
	.short	65535
	.short	1181
	.short	1117
	.short	1165
	.short	1025
	.short	1153
	.short	1307
	.short	1435
	.short	1492
	.short	65535
	.short	65535
	.short	1628
	.short	1688
	.short	1620
	.short	1665
	.short	65535
	.short	2012
	.short	1947
	.short	1939
	.short	65535
	.short	65535
	.short	221
	.short	27
	.short	207
	.short	65
	.short	193
	.short	412
	.short	281
	.short	467
	.short	449
	.short	65535
	.short	605
	.short	538
	.short	659
	.short	65535
	.short	65535
	.short	989
	.short	795
	.short	910
	.short	833
	.short	961
	.short	1055
	.short	1243
	.short	1103
	.short	1089
	.short	1217
	.short	1501
	.short	1495
	.short	1494
	.short	1345
	.short	1473
	.short	864
	.short	1690
	.short	1679
	.short	1601
	.short	1729
	.short	1823
	.short	1820
	.short	1807
	.short	1985
	.short	65535
	.short	18
	.short	80
	.short	12
	.short	72
	.short	65535
	.short	475
	.short	461
	.short	459
	.short	325
	.short	65535
	.short	725
	.short	528
	.short	712
	.short	648
	.short	65535
	.short	856
	.short	976
	.short	968
	.short	837
	.short	65535
	.short	1048
	.short	1104
	.short	1033
	.short	1028
	.short	65535
	.short	1303
	.short	1298
	.short	1355
	.short	1284
	.short	65535
	.short	1618
	.short	1614
	.short	1613
	.short	1547
	.short	65535
	.short	1874
	.short	1938
	.short	1933
	.short	1991
	.short	65535
	.short	145
	.short	208
	.short	10
	.short	74
	.short	65535
	.short	276
	.short	403
	.short	397
	.short	324
	.short	65535
	.short	604
	.short	526
	.short	585
	.short	709
	.short	65535
	.short	983
	.short	848
	.short	844
	.short	836
	.short	832
	.short	1175
	.short	1232
	.short	1035
	.short	1031
	.short	65535
	.short	1426
	.short	1423
	.short	1356
	.short	1289
	.short	1282
	.short	1687
	.short	1748
	.short	1673
	.short	1604
	.short	65535
	.short	1812
	.short	1810
	.short	1805
	.short	1925
	.short	65535
	.short	26
	.short	79
	.short	8
	.short	7
	.short	65535
	.short	160
	.short	463
	.short	390
	.short	453
	.short	320
	.short	658
	.short	720
	.short	523
	.short	520
	.short	65535
	.short	793
	.short	781
	.short	970
	.short	774
	.short	770
	.short	1049
	.short	1042
	.short	1095
	.short	1030
	.short	65535
	.short	1432
	.short	1485
	.short	1420
	.short	1412
	.short	1344
	.short	1619
	.short	1680
	.short	1615
	.short	1606
	.short	65535
	.short	1881
	.short	1868
	.short	1930
	.short	1799
	.short	1857
	.short	220
	.short	17
	.short	6
	.short	133
	.short	65535
	.short	476
	.short	333
	.short	267
	.short	260
	.short	65535
	.short	661
	.short	595
	.short	716
	.short	708
	.short	65535
	.short	921
	.short	909
	.short	973
	.short	773
	.short	65535
	.short	1241
	.short	1038
	.short	1101
	.short	1220
	.short	65535
	.short	1366
	.short	1361
	.short	1421
	.short	1476
	.short	65535
	.short	1756
	.short	1676
	.short	1740
	.short	1732
	.short	65535
	.short	1945
	.short	1870
	.short	1996
	.short	1797
	.short	65535
	.short	21
	.short	211
	.short	11
	.short	134
	.short	65535
	.short	272
	.short	400
	.short	332
	.short	457
	.short	65535
	.short	601
	.short	589
	.short	524
	.short	646
	.short	65535
	.short	789
	.short	786
	.short	779
	.short	838
	.short	65535
	.short	1045
	.short	1040
	.short	1230
	.short	1158
	.short	65535
	.short	1502
	.short	1487
	.short	1415
	.short	1287
	.short	65535
	.short	1563
	.short	1741
	.short	1610
	.short	1670
	.short	65535
	.short	1815
	.short	1875
	.short	1928
	.short	1863
	.short	65535
	.short	212
	.short	143
	.short	75
	.short	139
	.short	65535
	.short	473
	.short	335
	.short	396
	.short	452
	.short	65535
	.short	597
	.short	722
	.short	587
	.short	710
	.short	65535
	.short	790
	.short	915
	.short	906
	.short	966
	.short	65535
	.short	1171
	.short	1233
	.short	1097
	.short	1096
	.short	65535
	.short	1365
	.short	1293
	.short	1292
	.short	1354
	.short	65535
	.short	1559
	.short	1616
	.short	1611
	.short	1734
	.short	65535
	.short	1818
	.short	1878
	.short	1988
	.short	1860
	.short	65535
	.short	154
	.short	14
	.short	76
	.short	132
	.short	65535
	.short	282
	.short	270
	.short	395
	.short	261
	.short	65535
	.short	667
	.short	717
	.short	652
	.short	516
	.short	65535
	.short	917
	.short	908
	.short	972
	.short	971
	.short	65535
	.short	1110
	.short	1170
	.short	1163
	.short	1222
	.short	65535
	.short	1304
	.short	1360
	.short	1352
	.short	1477
	.short	65535
	.short	1691
	.short	1553
	.short	1735
	.short	1541
	.short	65535
	.short	2005
	.short	1806
	.short	1931
	.short	1867
	.short	65535
	.short	149
	.short	213
	.short	201
	.short	70
	.short	65535
	.short	471
	.short	398
	.short	334
	.short	391
	.short	321
	.short	731
	.short	593
	.short	647
	.short	581
	.short	65535
	.short	923
	.short	981
	.short	964
	.short	772
	.short	65535
	.short	1177
	.short	1237
	.short	1157
	.short	1093
	.short	65535
	.short	1493
	.short	1299
	.short	1418
	.short	1349
	.short	1281
	.short	1692
	.short	1739
	.short	1546
	.short	1543
	.short	65535
	.short	1817
	.short	1934
	.short	1804
	.short	1861
	.short	65535
	.short	152
	.short	142
	.short	203
	.short	135
	.short	65535
	.short	278
	.short	336
	.short	266
	.short	455
	.short	387
	.short	533
	.short	590
	.short	715
	.short	522
	.short	65535
	.short	852
	.short	850
	.short	780
	.short	902
	.short	65535
	.short	1046
	.short	1036
	.short	1164
	.short	1227
	.short	65535
	.short	1430
	.short	1358
	.short	1290
	.short	1482
	.short	65535
	.short	1623
	.short	1681
	.short	1609
	.short	1671
	.short	65535
	.short	1940
	.short	2003
	.short	1802
	.short	1927
	.short	65535
	.short	155
	.short	205
	.short	204
	.short	4
	.short	65535
	.short	277
	.short	399
	.short	268
	.short	328
	.short	65535
	.short	529
	.short	656
	.short	586
	.short	650
	.short	65535
	.short	788
	.short	787
	.short	907
	.short	967
	.short	65535
	.short	1234
	.short	1169
	.short	1225
	.short	1161
	.short	65535
	.short	1372
	.short	1489
	.short	1479
	.short	1348
	.short	65535
	.short	1753
	.short	1612
	.short	1544
	.short	1672
	.short	65535
	.short	1877
	.short	2004
	.short	1866
	.short	1989
	.short	65535
	.short	156
	.short	78
	.short	200
	.short	197
	.short	65535
	.short	406
	.short	337
	.short	331
	.short	262
	.short	65535
	.short	536
	.short	531
	.short	711
	.short	518
	.short	65535
	.short	918
	.short	846
	.short	778
	.short	969
	.short	834
	.short	1115
	.short	1231
	.short	1224
	.short	1094
	.short	65535
	.short	1300
	.short	1364
	.short	1483
	.short	1285
	.short	65535
	.short	1556
	.short	1555
	.short	1674
	.short	1542
	.short	1667
	.short	1942
	.short	1872
	.short	1932
	.short	1798
	.short	65535
	.short	88
	.short	15
	.short	140
	.short	69
	.short	65535
	.short	341
	.short	275
	.short	394
	.short	326
	.short	65535
	.short	726
	.short	657
	.short	714
	.short	582
	.short	512
	.short	849
	.short	913
	.short	974
	.short	839
	.short	897
	.short	1109
	.short	1106
	.short	1226
	.short	1223
	.short	65535
	.short	1362
	.short	1488
	.short	1295
	.short	1350
	.short	1475
	.short	1755
	.short	1548
	.short	1738
	.short	1607
	.short	65535
	.short	1882
	.short	2002
	.short	1926
	.short	1862
	.short	65535
	.short	25
	.short	202
	.short	9
	.short	136
	.short	65535
	.short	340
	.short	465
	.short	264
	.short	392
	.short	65535
	.short	535
	.short	653
	.short	651
	.short	521
	.short	65535
	.short	916
	.short	912
	.short	841
	.short	904
	.short	65535
	.short	1235
	.short	1168
	.short	1098
	.short	1160
	.short	65535
	.short	1431
	.short	1294
	.short	1291
	.short	1416
	.short	65535
	.short	1557
	.short	1551
	.short	1675
	.short	1608
	.short	1602
	.short	1941
	.short	1998
	.short	1803
	.short	1994
	.short	65535
	.short	89
	.short	138
	.short	73
	.short	137
	.short	65535
	.short	279
	.short	271
	.short	329
	.short	456
	.short	448
	.short	662
	.short	525
	.short	588
	.short	713
	.short	65535
	.short	857
	.short	843
	.short	777
	.short	776
	.short	65535
	.short	1236
	.short	1044
	.short	1162
	.short	1159
	.short	65535
	.short	1434
	.short	1481
	.short	1353
	.short	1417
	.short	65535
	.short	1747
	.short	1678
	.short	1550
	.short	1736
	.short	1539
	.short	1873
	.short	1809
	.short	1865
	.short	1992
	.short	1921
	.short	24
	.short	22
	.short	5
	.short	196
	.short	65535
	.short	348
	.short	460
	.short	393
	.short	263
	.short	65535
	.short	665
	.short	719
	.short	649
	.short	519
	.short	65535
	.short	859
	.short	845
	.short	905
	.short	775
	.short	65535
	.short	1180
	.short	1100
	.short	1228
	.short	1156
	.short	65535
	.short	1496
	.short	1429
	.short	1414
	.short	1413
	.short	65535
	.short	1689
	.short	1549
	.short	1677
	.short	1605
	.short	65535
	.short	1816
	.short	1808
	.short	1929
	.short	1924
	.short	65535
	.short	20
	.short	209
	.short	13
	.short	71
	.short	65535
	.short	472
	.short	458
	.short	330
	.short	265
	.short	65535
	.short	729
	.short	660
	.short	583
	.short	580
	.short	65535
	.short	985
	.short	980
	.short	903
	.short	900
	.short	65535
	.short	1239
	.short	1105
	.short	1229
	.short	1092
	.short	65535
	.short	1301
	.short	1297
	.short	1419
	.short	1351
	.short	65535
	.short	1560
	.short	1552
	.short	1737
	.short	1668
	.short	65535
	.short	1880
	.short	1995
	.short	1993
	.short	1801
	.short	65535
	.short	19
	.short	210
	.short	141
	.short	68
	.short	194
	.short	408
	.short	402
	.short	327
	.short	389
	.short	386
	.short	539
	.short	724
	.short	517
	.short	644
	.short	65535
	.short	982
	.short	975
	.short	842
	.short	840
	.short	768
	.short	1176
	.short	1099
	.short	1034
	.short	1032
	.short	65535
	.short	1305
	.short	1484
	.short	1288
	.short	1480
	.short	65535
	.short	1750
	.short	1749
	.short	1545
	.short	1540
	.short	65535
	.short	1944
	.short	1876
	.short	1990
	.short	1796
	.short	1793
	.short	216
	.short	82
	.short	199
	.short	198
	.short	64
	.short	474
	.short	468
	.short	454
	.short	388
	.short	65535
	.short	728
	.short	592
	.short	584
	.short	645
	.short	65535
	.short	924
	.short	914
	.short	901
	.short	965
	.short	65535
	.short	1240
	.short	1174
	.short	1029
	.short	1221
	.short	65535
	.short	1433
	.short	1491
	.short	1478
	.short	1286
	.short	65535
	.short	1752
	.short	1558
	.short	1669
	.short	1733
	.short	65535
	.short	2008
	.short	1997
	.short	1864
	.short	1800
	.short	65535
	.size	_ZL7idx_tab, 2560

	.type	__hip_cuid_794236f6d9ab0dff,@object
